# first XCD barrier: the 16 serialized census loads (workgroups per XCD) issued together before one wait
# speedup vs baseline: 1.0010x; 1.0010x over previous
; __device__ __forceinline__ unsigned xb_ld(unsigned* p)              { return __hip_atomic_load(p, __ATOMIC_RELAXED, __HIP_MEMORY_SCOPE_AGENT); }
; __device__ __forceinline__ void xcd_barrier_complete(unsigned* bar, unsigned x, unsigned& nloc, unsigned& nx) {
;     ...
;     for (;;) {
;         sum = 0u; cnt = 0u; mine = 0u;
; #pragma unroll
;         for (unsigned j = 0; j < 16; ++j) { const unsigned c = xb_ld(&bar[XB_XCNT(j)]); sum += c; cnt += (c > 0u) ? 1u : 0u; mine = (j == x) ? c : mine; }
;         if (sum == G) break;
;         __builtin_amdgcn_s_sleep(1);
;         if ((++sp & 255u) == 0u) { if (xb_ld(&bar[XB_TMO])) break; if (sp > XB_SPIN_CAP) { atomicAdd(&bar[XB_TMO], 1u); break; } }
;     }
.LBB0_419:
	v_readlane_b32 s6, v242, 32
	v_readlane_b32 s7, v242, 33
	v_readlane_b32 s8, v242, 29
	s_waitcnt lgkmcnt(0)
	s_nop 4
	global_load_dword v0, v16, s[6:7] sc1
	global_load_dword v1, v16, s[6:7] offset:256 sc1
	global_load_dword v2, v16, s[6:7] offset:512 sc1
	global_load_dword v3, v16, s[6:7] offset:768 sc1
	global_load_dword v4, v16, s[6:7] offset:1024 sc1
	global_load_dword v5, v16, s[6:7] offset:1280 sc1
	global_load_dword v6, v16, s[6:7] offset:1536 sc1
	global_load_dword v7, v16, s[6:7] offset:1792 sc1
	global_load_dword v8, v16, s[6:7] offset:2048 sc1
	global_load_dword v9, v16, s[6:7] offset:2304 sc1
	global_load_dword v10, v16, s[6:7] offset:2560 sc1
	global_load_dword v11, v16, s[6:7] offset:2816 sc1
	global_load_dword v12, v16, s[6:7] offset:3072 sc1
	global_load_dword v13, v16, s[6:7] offset:3328 sc1
	global_load_dword v14, v16, s[6:7] offset:3584 sc1
	global_load_dword v15, v16, s[6:7] offset:3840 sc1
	s_waitcnt vmcnt(0)
	v_add_u32_e32 v17, v1, v0
	v_add3_u32 v17, v17, v2, v3
	v_add3_u32 v17, v17, v4, v5
	v_add3_u32 v17, v17, v6, v7
	v_add3_u32 v17, v17, v8, v9
	v_add3_u32 v17, v17, v10, v11
	v_add3_u32 v17, v17, v12, v13
	v_add3_u32 v17, v17, v14, v15
	s_mov_b64 s[6:7], -1
	v_cmp_eq_u32_e32 vcc, s8, v17
	s_mov_b64 s[8:9], -1
	s_cbranch_vccnz .LBB0_418
	s_and_b32 s6, s12, 0xff
	s_cmp_eq_u32 s6, 0
	s_mov_b64 s[6:7], -1
	s_mov_b64 s[10:11], -1
	s_sleep 1
	s_cbranch_scc1 .LBB0_423
	s_and_b64 vcc, exec, s[10:11]
	s_cbranch_vccz .LBB0_418
